# hyena output section (order-2 path): the eight per-group z1 reloads, serialised load-wait-store by the compiler, issued together at the first group into registers only the order-1 path uses
# speedup vs baseline: 1.0112x; 1.0112x over previous
; #define HY_FRESH() do { tid = fresh_tid(wave_id); xc = X + 33 * tid; n0 = 32 * tid; } while (0)
; template <int MODE> __device__ __forceinline__ void hyena_unit(KP p, int pair, float2* X, int wave_id) {
;     ...
;         HY_FRESH();
;         const Row32 rga = ld_row32(ga + n0), rgb = ld_row32(gb + n0);
;         float lga, rga_, lgb, rgb_; row_edges(ga, tid, cga.ib, lga, rga_); row_edges(gb, tid, cgb.ib, lgb, rgb_);
;         Row32 ra, rb; float la = 0.f, ra_ = 0.f, lb = 0.f, rb_ = 0.f;
;         if (ord == 0) { ra = ld_row32(va + n0); rb = ld_row32(vb + n0); row_edges(va, tid, cva.ib, la, ra_); row_edges(vb, tid, cvb.ib, lb, rb_); }
;         u32x4 ylast;
;         asm volatile("global_load_dwordx4 %0, %1, off sc0 sc1\n\ts_waitcnt vmcnt(0)" : "=&v"(ylast) : "v"(YE + n0 + 28) : "memory");
; #pragma unroll
;         for (int g = 0; g < 8; ++g) {
;           f32x4 ua4, ub4;
;           if (ord == 0) {
; #pragma unroll
;             for (int k = 0; k < 4; ++k) { ua4[k] = conv_at(ra, 4 * g + k, la, ra_, cva); ub4[k] = conv_at(rb, 4 * g + k, lb, rb_, cvb); }
;           } else { float a[4], b[4]; unpack4(*(const u32x2*)(za + n0 + 4 * g), a); unpack4(*(const u32x2*)(zb + n0 + 4 * g), b);
; #pragma unroll
;             for (int k = 0; k < 4; ++k) { ua4[k] = a[k]; ub4[k] = b[k]; } }
;           const u32x4 yew = (g < 7) ? yreg[g < 7 ? g : 0] : ylast;
.LBB0_125:
	v_readlane_b32 s12, v254, 35
	v_readlane_b32 s13, v254, 36
	s_and_b64 vcc, exec, s[22:23]
	s_nop 0
	v_lshl_add_u64 v[72:73], v[114:115], 2, s[12:13]
	s_mov_b64 s[12:13], 0x70
	v_lshl_add_u64 v[94:95], v[72:73], 0, s[12:13]
	v_readlane_b32 s12, v254, 41
	v_readlane_b32 s13, v254, 42
	global_load_dwordx4 v[72:75], v[94:95], off sc0 sc1
	s_waitcnt vmcnt(0)
	s_nop 1
	v_lshl_add_u64 v[116:117], s[12:13], 0, v[92:93]
	v_readlane_b32 s12, v254, 52
	v_readlane_b32 s13, v254, 53
	s_nop 1
	v_lshl_add_u64 v[118:119], s[12:13], 0, v[92:93]
	s_mov_b64 s[12:13], -1
	s_cbranch_vccz .LBB0_127
	global_load_dwordx2 v[104:105], v[116:117], off
	global_load_dwordx2 v[106:107], v[118:119], off
	global_load_dwordx2 v[32:33], v[116:117], off offset:8
	global_load_dwordx2 v[34:35], v[118:119], off offset:8
	global_load_dwordx2 v[36:37], v[116:117], off offset:16
	global_load_dwordx2 v[38:39], v[118:119], off offset:16
	global_load_dwordx2 v[40:41], v[116:117], off offset:24
	global_load_dwordx2 v[42:43], v[118:119], off offset:24
	global_load_dwordx2 v[44:45], v[116:117], off offset:32
	global_load_dwordx2 v[46:47], v[118:119], off offset:32
	global_load_dwordx2 v[48:49], v[116:117], off offset:40
	global_load_dwordx2 v[50:51], v[118:119], off offset:40
	global_load_dwordx2 v[52:53], v[116:117], off offset:48
	global_load_dwordx2 v[54:55], v[118:119], off offset:48
	global_load_dwordx2 v[56:57], v[116:117], off offset:56
	global_load_dwordx2 v[58:59], v[118:119], off offset:56
	s_mov_b64 s[12:13], 0
	s_waitcnt vmcnt(15)
	v_lshlrev_b32_e32 v93, 16, v104
	v_and_b32_e32 v95, 0xffff0000, v104
	v_lshlrev_b32_e32 v133, 16, v105
	v_and_b32_e32 v131, 0xffff0000, v105
	s_waitcnt vmcnt(14)
	v_lshlrev_b32_e32 v104, 16, v106
	v_and_b32_e32 v105, 0xffff0000, v106
	v_lshlrev_b32_e32 v106, 16, v107
	v_and_b32_e32 v107, 0xffff0000, v107

; __device__ __forceinline__ unsigned cvt_pk_bf16(float lo, float hi) { unsigned r; asm volatile("v_cvt_pk_bf16_f32 %0, %1, %2" : "=v"(r) : "v"(lo), "v"(hi)); return r; }
; __device__ __forceinline__ float hw_sin_rev(float r) { return __builtin_amdgcn_sinf(r); }
; __device__ __forceinline__ float hw_cos_rev(float r) { return __builtin_amdgcn_cosf(r); }
; __device__ __forceinline__ float2 cmul(float2 a, float2 b) { return make_float2(a.x * b.x - a.y * b.y, a.x * b.y + a.y * b.x); }
; __device__ __forceinline__ float2 unpack_h2(unsigned w) { return make_float2(__uint_as_float(w << 16), __uint_as_float(w & 0xffff0000u)); }
; template <int MODE> __device__ __forceinline__ void hyena_unit(KP p, int pair, float2* X, int wave_id) {
;     ...
;           } else { float a[4], b[4]; unpack4(*(const u32x2*)(za + n0 + 4 * g), a); unpack4(*(const u32x2*)(zb + n0 + 4 * g), b);
; #pragma unroll
;             for (int k = 0; k < 4; ++k) { ua4[k] = a[k]; ub4[k] = b[k]; } }
;           const u32x4 yew = (g < 7) ? yreg[g < 7 ? g : 0] : ylast;
;           f32x4 oa, ob;
; #pragma unroll
;           for (int k = 0; k < 4; ++k) {
;             const int c = 4 * g + k;
;             const float r = (float)(n0 + c) * invN;
;             const float2 yo = cmul(make_float2(hw_cos_rev(r), hw_sin_rev(r)), xc[c]);
;             const float2 ye = unpack_h2(yew[k]);
;             const float ya = ye.x + yo.x * (16.0f * invN), yb = ye.y + yo.y * (16.0f * invN);
;             oa[k] = conv_at(rga, c, lga, rga_, cga) * (ya + ska * ua4[k]);
;             ob[k] = conv_at(rgb, c, lgb, rgb_, cgb) * (yb + skb * ub4[k]);
;           }
;           { u32x2 wa, wb; wa.x = cvt_pk_bf16(oa[0], oa[1]); wa.y = cvt_pk_bf16(oa[2], oa[3]); wb.x = cvt_pk_bf16(ob[0], ob[1]); wb.y = cvt_pk_bf16(ob[2], ob[3]);
;             *(u32x2*)(za + n0 + 4 * g) = wa; *(u32x2*)(zb + n0 + 4 * g) = wb; }
.LBB0_129:
	v_cvt_f32_i32_e32 v108, v114
	s_movk_i32 s12, 0x108
	v_mul_lo_u32 v92, v120, s12
	v_lshlrev_b32_e32 v109, 16, v122
	v_add_u32_e32 v115, 0, v92
	v_add_f32_e32 v120, s65, v109
	v_mul_f32_e32 v122, 0x38000000, v108
	ds_read2_b64 v[108:111], v115 offset1:1
	ds_read2_b64 v[148:151], v115 offset0:2 offset1:3
	v_lshlrev_b32_e32 v94, 16, v128
	v_cos_f32_e32 v128, v122
	v_sin_f32_e32 v129, v122
	v_add_f32_e32 v94, s59, v94
	v_cndmask_b32_e64 v94, 0, v94, s[10:11]
	s_waitcnt lgkmcnt(1)
	v_mul_f32_e32 v92, v128, v108
	v_pk_fma_f32 v[140:141], v[128:129], v[108:109], v[92:93] op_sel_hi:[1,1,0] neg_lo:[1,0,0] neg_hi:[1,0,0]
	v_and_b32_e32 v92, 0xffff0000, v100
	v_lshlrev_b32_e32 v100, 16, v100
	v_mul_f32_e32 v109, v128, v109
	v_mul_f32_e32 v122, v129, v108
	v_lshlrev_b32_e32 v129, 16, v147
	v_add_f32_e32 v140, s59, v100
	v_mul_f32_e32 v128, s96, v94
	v_add_f32_e32 v92, s59, v92
	v_pk_fma_f32 v[128:129], s[34:35], v[140:141], v[128:129]
	v_cndmask_b32_e64 v120, 0, v120, s[10:11]
	v_pk_fma_f32 v[128:129], s[40:41], v[92:93], v[128:129]
	v_or_b32_e32 v93, 1, v114
	v_cvt_f32_i32_e32 v93, v93
	v_add_f32_e32 v94, s93, v128
	v_mul_f32_e32 v124, v94, v129
	v_mul_f32_e32 v152, s26, v120
	v_mul_f32_e32 v93, 0x38000000, v93
	v_cos_f32_e32 v154, v93
	v_sin_f32_e32 v155, v93
	v_lshlrev_b32_e32 v93, 16, v101
	v_and_b32_e32 v128, 0xffff0000, v96
	v_mul_f32_e32 v94, v154, v110
	v_pk_fma_f32 v[156:157], v[154:155], v[110:111], v[94:95] op_sel_hi:[1,1,0] neg_lo:[1,0,0] neg_hi:[1,0,0]
	v_mov_b32_e32 v158, v155
	v_mov_b32_e32 v159, v154
	v_mul_f32_e32 v94, v155, v110
	v_pk_fma_f32 v[110:111], v[158:159], v[110:111], v[94:95] op_sel_hi:[1,1,0]
	v_add_f32_e32 v94, s59, v93
	v_or_b32_e32 v93, 2, v114
	v_cvt_f32_i32_e32 v93, v93
	v_lshlrev_b32_e32 v155, 16, v190
	v_mul_f32_e32 v154, s34, v92
	v_mov_b32_e32 v141, v157
	v_mul_f32_e32 v93, 0x38000000, v93
	v_pk_fma_f32 v[140:141], s[96:97], v[140:141], v[154:155]
	v_cos_f32_e32 v154, v93
	v_sin_f32_e32 v155, v93
	v_pk_fma_f32 v[140:141], s[40:41], v[94:95], v[140:141]
	v_and_b32_e32 v93, 0xffff0000, v101
	v_add_f32_e32 v95, s93, v140
	s_waitcnt lgkmcnt(0)
	v_mul_f32_e32 v100, v154, v148
	v_mul_f32_e32 v120, v95, v141
	v_pk_fma_f32 v[140:141], v[154:155], v[148:149], v[100:101] op_sel_hi:[1,1,0] neg_lo:[1,0,0] neg_hi:[1,0,0]
	v_mul_f32_e32 v129, v154, v149
	v_mul_f32_e32 v149, v155, v148
	v_lshlrev_b32_e32 v155, 16, v191
	v_add_f32_e32 v132, s59, v93
	v_mul_f32_e32 v154, s34, v94
	v_mov_b32_e32 v93, v141
	v_pk_fma_f32 v[92:93], s[96:97], v[92:93], v[154:155]
	v_mov_b32_e32 v148, s65
	v_pk_fma_f32 v[92:93], s[40:41], v[132:133], v[92:93]
	v_lshlrev_b32_e32 v108, 16, v96
	v_add_f32_e32 v92, s93, v92
	v_mul_f32_e32 v126, v92, v93
	v_or_b32_e32 v93, 3, v114
	v_cvt_f32_i32_e32 v93, v93
	v_pk_add_f32 v[100:101], v[148:149], v[128:129]
	v_mov_b32_e32 v149, v122
	v_and_b32_e32 v153, 0xffff0000, v147
	v_pk_add_f32 v[108:109], v[148:149], v[108:109]
	v_mov_b32_e32 v140, v100
	v_pk_fma_f32 v[128:129], s[94:95], v[108:109], v[152:153]
	v_mov_b32_e32 v141, v104
	v_pk_fma_f32 v[128:129], s[46:47], v[140:141], v[128:129]
	v_mul_f32_e32 v93, 0x38000000, v93
	v_add_f32_e32 v95, s55, v128
	v_cos_f32_e32 v128, v93
	v_mul_f32_e32 v122, v95, v129
	v_sin_f32_e32 v129, v93
	v_lshlrev_b32_e32 v95, 16, v102
	v_mul_f32_e32 v104, v128, v150
	v_lshlrev_b32_e32 v96, 16, v97
	v_pk_fma_f32 v[140:141], v[128:129], v[150:151], v[104:105] op_sel_hi:[1,1,0] neg_lo:[1,0,0] neg_hi:[1,0,0]
	v_and_b32_e32 v92, 0xffff0000, v97
	v_mul_f32_e32 v97, v128, v151
	v_mul_f32_e32 v149, v129, v150
	v_lshlrev_b32_e32 v129, 16, v192
	v_add_f32_e32 v130, s59, v95
	v_mul_f32_e32 v128, s34, v132
	v_mov_b32_e32 v95, v141
	v_pk_fma_f32 v[94:95], s[96:97], v[94:95], v[128:129]
	v_and_b32_e32 v159, 0xffff0000, v190
	v_pk_fma_f32 v[94:95], s[40:41], v[130:131], v[94:95]
	v_mul_f32_e32 v158, s94, v100
	v_add_f32_e32 v94, s93, v94
	v_mul_f32_e32 v128, v94, v95
	v_lshlrev_b32_e32 v94, 16, v98
	v_mov_b32_e32 v93, v106
	v_add_f32_e32 v106, s65, v94
	v_pk_add_f32 v[94:95], v[148:149], v[96:97]
	v_mov_b32_e32 v110, s26
	v_mov_b32_e32 v109, 0x3a000000
	v_pk_fma_f32 v[96:97], v[110:111], v[108:109], v[158:159]
	v_mov_b32_e32 v104, v94
	v_add_f32_e32 v92, s65, v92
	v_pk_fma_f32 v[96:97], s[46:47], v[104:105], v[96:97]
	v_and_b32_e32 v157, 0xffff0000, v191
	v_and_b32_e32 v151, 0xffff0000, v192
	v_mul_f32_e32 v150, s94, v92
	v_mul_f32_e32 v156, s94, v94
	v_add_f32_e32 v96, s55, v96
	v_mul_f32_e32 v104, v96, v97
	v_pk_fma_f32 v[96:97], s[26:27], v[100:101], v[156:157]
	v_pk_fma_f32 v[94:95], s[26:27], v[94:95], v[150:151]
	v_pk_fma_f32 v[96:97], s[46:47], v[92:93], v[96:97]
	v_pk_fma_f32 v[94:95], s[46:47], v[106:107], v[94:95]
	v_add_f32_e32 v93, s55, v96
	v_add_f32_e32 v94, s55, v94
	v_mul_f32_e32 v93, v93, v97
	v_mul_f32_e32 v97, v94, v95
	v_cvt_pk_bf16_f32 v94, v124, v120
	v_cvt_pk_bf16_f32 v95, v126, v128
	v_cvt_pk_bf16_f32 v96, v122, v104
	v_cvt_pk_bf16_f32 v97, v93, v97
	s_and_b64 vcc, exec, s[6:7]
	s_mov_b64 s[10:11], -1
	global_store_dwordx2 v[116:117], v[94:95], off
	global_store_dwordx2 v[118:119], v[96:97], off
	s_cbranch_vccnz .LBB0_131
	v_mov_b32_e32 v94, v32
	v_mov_b32_e32 v95, v33
	v_mov_b32_e32 v96, v34
	v_mov_b32_e32 v97, v35
	s_mov_b64 s[10:11], 0
	s_nop 0
	v_lshlrev_b32_e32 v108, 16, v94
	v_and_b32_e32 v109, 0xffff0000, v94
	v_lshlrev_b32_e32 v110, 16, v95
	v_and_b32_e32 v111, 0xffff0000, v95
	s_nop 0
	v_lshlrev_b32_e32 v94, 16, v96
	v_and_b32_e32 v95, 0xffff0000, v96
	v_lshlrev_b32_e32 v96, 16, v97
	v_and_b32_e32 v97, 0xffff0000, v97

; __device__ __forceinline__ unsigned cvt_pk_bf16(float lo, float hi) { unsigned r; asm volatile("v_cvt_pk_bf16_f32 %0, %1, %2" : "=v"(r) : "v"(lo), "v"(hi)); return r; }
; __device__ __forceinline__ float hw_sin_rev(float r) { return __builtin_amdgcn_sinf(r); }
; __device__ __forceinline__ float hw_cos_rev(float r) { return __builtin_amdgcn_cosf(r); }
; __device__ __forceinline__ float2 cmul(float2 a, float2 b) { return make_float2(a.x * b.x - a.y * b.y, a.x * b.y + a.y * b.x); }
; __device__ __forceinline__ float2 unpack_h2(unsigned w) { return make_float2(__uint_as_float(w << 16), __uint_as_float(w & 0xffff0000u)); }
; template <int MODE> __device__ __forceinline__ void hyena_unit(KP p, int pair, float2* X, int wave_id) {
;     ...
;           } else { float a[4], b[4]; unpack4(*(const u32x2*)(za + n0 + 4 * g), a); unpack4(*(const u32x2*)(zb + n0 + 4 * g), b);
; #pragma unroll
;             for (int k = 0; k < 4; ++k) { ua4[k] = a[k]; ub4[k] = b[k]; } }
;           const u32x4 yew = (g < 7) ? yreg[g < 7 ? g : 0] : ylast;
;           f32x4 oa, ob;
; #pragma unroll
;           for (int k = 0; k < 4; ++k) {
;             const int c = 4 * g + k;
;             const float r = (float)(n0 + c) * invN;
;             const float2 yo = cmul(make_float2(hw_cos_rev(r), hw_sin_rev(r)), xc[c]);
;             const float2 ye = unpack_h2(yew[k]);
;             const float ya = ye.x + yo.x * (16.0f * invN), yb = ye.y + yo.y * (16.0f * invN);
;             oa[k] = conv_at(rga, c, lga, rga_, cga) * (ya + ska * ua4[k]);
;             ob[k] = conv_at(rgb, c, lgb, rgb_, cgb) * (yb + skb * ub4[k]);
;           }
;           { u32x2 wa, wb; wa.x = cvt_pk_bf16(oa[0], oa[1]); wa.y = cvt_pk_bf16(oa[2], oa[3]); wb.x = cvt_pk_bf16(ob[0], ob[1]); wb.y = cvt_pk_bf16(ob[2], ob[3]);
;             *(u32x2*)(za + n0 + 4 * g) = wa; *(u32x2*)(zb + n0 + 4 * g) = wb; }
.LBB0_133:
	v_or_b32_e32 v93, 4, v114
	v_cvt_f32_i32_e32 v93, v93
	ds_read2_b64 v[150:153], v115 offset0:4 offset1:5
	v_and_b32_e32 v148, 0xffff0000, v98
	v_lshlrev_b32_e32 v131, 16, v194
	v_mul_f32_e32 v93, 0x38000000, v93
	v_cos_f32_e32 v100, v93
	v_sin_f32_e32 v101, v93
	v_and_b32_e32 v93, 0xffff0000, v102
	v_lshlrev_b32_e32 v157, 16, v195
	s_waitcnt lgkmcnt(0)
	v_mul_f32_e32 v120, v100, v150
	v_pk_fma_f32 v[140:141], v[100:101], v[150:151], v[120:121] op_sel_hi:[1,1,0] neg_lo:[1,0,0] neg_hi:[1,0,0]
	v_mov_b32_e32 v134, v101
	v_mov_b32_e32 v135, v100
	v_mul_f32_e32 v100, v101, v150
	v_pk_fma_f32 v[136:137], v[134:135], v[150:151], v[100:101] op_sel_hi:[1,1,0]
	v_lshlrev_b32_e32 v101, 16, v193
	v_mul_f32_e32 v100, s34, v130
	v_mov_b32_e32 v133, v141
	v_add_f32_e32 v150, s59, v93
	v_pk_fma_f32 v[100:101], s[96:97], v[132:133], v[100:101]
	v_mov_b32_e32 v151, v108
	v_pk_fma_f32 v[100:101], s[40:41], v[150:151], v[100:101]
	v_mul_f32_e32 v130, s96, v130
	v_add_f32_e32 v93, s93, v100
	v_mul_f32_e32 v105, v93, v101
	v_or_b32_e32 v93, 5, v114
	v_cvt_f32_i32_e32 v93, v93
	v_and_b32_e32 v135, 0xffff0000, v193
	v_mul_f32_e32 v134, s94, v106
	v_and_b32_e32 v159, 0xffff0000, v195
	v_mul_f32_e32 v93, 0x38000000, v93
	v_cos_f32_e32 v100, v93
	v_sin_f32_e32 v101, v93
	v_lshlrev_b32_e32 v93, 16, v103
	v_add_f32_e32 v108, s59, v93
	v_mul_f32_e32 v98, v100, v152
	v_pk_fma_f32 v[140:141], v[100:101], v[152:153], v[98:99] op_sel_hi:[1,1,0] neg_lo:[1,0,0] neg_hi:[1,0,0]
	v_mov_b32_e32 v132, v101
	v_mov_b32_e32 v151, v141
	v_pk_fma_f32 v[130:131], s[34:35], v[150:151], v[130:131]
	v_mov_b32_e32 v133, v100
	v_pk_fma_f32 v[130:131], s[40:41], v[108:109], v[130:131]
	v_mul_f32_e32 v98, v101, v152
	v_add_f32_e32 v93, s93, v130
	v_mul_f32_e32 v120, v93, v131
	v_or_b32_e32 v93, 6, v114
	v_cvt_f32_i32_e32 v93, v93
	v_pk_fma_f32 v[132:133], v[132:133], v[152:153], v[98:99] op_sel_hi:[1,1,0]
	ds_read2_b64 v[152:155], v115 offset0:6 offset1:7
	v_and_b32_e32 v101, 0xffff0000, v194
	v_mul_f32_e32 v93, 0x38000000, v93
	v_cos_f32_e32 v130, v93
	v_sin_f32_e32 v131, v93
	v_and_b32_e32 v93, 0xffff0000, v103
	v_mul_f32_e32 v156, s34, v108
	s_waitcnt lgkmcnt(0)
	v_mul_f32_e32 v100, v130, v152
	v_pk_fma_f32 v[140:141], v[130:131], v[152:153], v[100:101] op_sel_hi:[1,1,0] neg_lo:[1,0,0] neg_hi:[1,0,0]
	v_mul_f32_e32 v149, v130, v153
	v_mov_b32_e32 v151, v141
	v_mul_f32_e32 v131, v131, v152
	v_add_f32_e32 v152, s59, v93
	v_pk_fma_f32 v[102:103], s[96:97], v[150:151], v[156:157]
	v_mov_b32_e32 v153, v110
	v_pk_fma_f32 v[102:103], s[40:41], v[152:153], v[102:103]
	v_mov_b32_e32 v130, s65
	v_add_f32_e32 v93, s93, v102
	v_mul_f32_e32 v122, v93, v103
	v_and_b32_e32 v93, 0xffff0000, v99
	v_add_f32_e32 v102, s65, v93
	v_pk_add_f32 v[140:141], v[130:131], v[148:149]
	v_mov_b32_e32 v93, v137
	v_pk_fma_f32 v[92:93], s[26:27], v[92:93], v[134:135]
	v_mov_b32_e32 v134, v140
	v_mov_b32_e32 v135, v94
	v_pk_fma_f32 v[92:93], s[46:47], v[134:135], v[92:93]
	v_lshlrev_b32_e32 v98, 16, v99
	v_add_f32_e32 v92, s55, v92
	v_mul_f32_e32 v125, v92, v93
	v_or_b32_e32 v92, 7, v114
	v_cvt_f32_i32_e32 v92, v92
	v_mul_f32_e32 v100, s94, v140
	v_mov_b32_e32 v103, v96
	v_mov_b32_e32 v107, v133
	v_mul_f32_e32 v93, 0x38000000, v92
	v_cos_f32_e32 v92, v93
	v_sin_f32_e32 v93, v93
	v_and_b32_e32 v137, 0xffff0000, v196
	v_mul_f32_e32 v136, s94, v102
	v_mul_f32_e32 v94, v92, v154
	v_pk_fma_f32 v[134:135], v[92:93], v[154:155], v[94:95] op_sel_hi:[1,1,0] neg_lo:[1,0,0] neg_hi:[1,0,0]
	v_mul_f32_e32 v99, v92, v155
	v_lshlrev_b32_e32 v92, 16, v88
	v_mul_f32_e32 v131, v93, v154
	v_lshlrev_b32_e32 v93, 16, v196
	v_add_f32_e32 v110, s59, v92
	v_mul_f32_e32 v92, s34, v152
	v_mov_b32_e32 v109, v135
	v_pk_fma_f32 v[92:93], s[96:97], v[108:109], v[92:93]
	s_mov_b64 s[10:11], -1
	v_pk_fma_f32 v[92:93], s[40:41], v[110:111], v[92:93]
	s_and_b64 vcc, exec, s[6:7]
	v_add_f32_e32 v92, s93, v92
	v_mul_f32_e32 v108, v92, v93
	v_lshlrev_b32_e32 v92, 16, v84
	v_add_f32_e32 v96, s65, v92
	v_pk_add_f32 v[92:93], v[130:131], v[98:99]
	v_pk_fma_f32 v[98:99], s[26:27], v[106:107], v[100:101]
	v_mov_b32_e32 v94, v92
	v_pk_fma_f32 v[94:95], s[46:47], v[94:95], v[98:99]
	v_mul_f32_e32 v158, s94, v92
	v_add_f32_e32 v94, s55, v94
	v_mul_f32_e32 v98, v94, v95
	v_pk_fma_f32 v[94:95], s[26:27], v[140:141], v[158:159]
	v_pk_fma_f32 v[92:93], s[26:27], v[92:93], v[136:137]
	v_pk_fma_f32 v[94:95], s[46:47], v[102:103], v[94:95]
	v_pk_fma_f32 v[92:93], s[46:47], v[96:97], v[92:93]
	v_add_f32_e32 v94, s55, v94
	v_mul_f32_e32 v95, v94, v95
	v_add_f32_e32 v92, s55, v92
	v_mul_f32_e32 v97, v92, v93
	v_cvt_pk_bf16_f32 v92, v105, v120
	v_cvt_pk_bf16_f32 v93, v122, v108
	v_cvt_pk_bf16_f32 v94, v125, v98
	v_cvt_pk_bf16_f32 v95, v95, v97
	global_store_dwordx2 v[116:117], v[92:93], off offset:8
	global_store_dwordx2 v[118:119], v[94:95], off offset:8
	s_cbranch_vccnz .LBB0_135
	v_mov_b32_e32 v92, v36
	v_mov_b32_e32 v93, v37
	v_mov_b32_e32 v94, v38
	v_mov_b32_e32 v95, v39
	s_mov_b64 s[10:11], 0
	s_nop 0
	v_lshlrev_b32_e32 v98, 16, v92
	v_and_b32_e32 v99, 0xffff0000, v92
	v_lshlrev_b32_e32 v100, 16, v93
	v_and_b32_e32 v101, 0xffff0000, v93
	s_nop 0
	v_lshlrev_b32_e32 v92, 16, v94
	v_and_b32_e32 v93, 0xffff0000, v94
	v_lshlrev_b32_e32 v94, 16, v95
	v_and_b32_e32 v95, 0xffff0000, v95

; __device__ __forceinline__ unsigned cvt_pk_bf16(float lo, float hi) { unsigned r; asm volatile("v_cvt_pk_bf16_f32 %0, %1, %2" : "=v"(r) : "v"(lo), "v"(hi)); return r; }
; __device__ __forceinline__ float hw_sin_rev(float r) { return __builtin_amdgcn_sinf(r); }
; __device__ __forceinline__ float hw_cos_rev(float r) { return __builtin_amdgcn_cosf(r); }
; __device__ __forceinline__ float2 cmul(float2 a, float2 b) { return make_float2(a.x * b.x - a.y * b.y, a.x * b.y + a.y * b.x); }
; __device__ __forceinline__ float2 unpack_h2(unsigned w) { return make_float2(__uint_as_float(w << 16), __uint_as_float(w & 0xffff0000u)); }
; template <int MODE> __device__ __forceinline__ void hyena_unit(KP p, int pair, float2* X, int wave_id) {
;     ...
;           } else { float a[4], b[4]; unpack4(*(const u32x2*)(za + n0 + 4 * g), a); unpack4(*(const u32x2*)(zb + n0 + 4 * g), b);
; #pragma unroll
;             for (int k = 0; k < 4; ++k) { ua4[k] = a[k]; ub4[k] = b[k]; } }
;           const u32x4 yew = (g < 7) ? yreg[g < 7 ? g : 0] : ylast;
;           f32x4 oa, ob;
; #pragma unroll
;           for (int k = 0; k < 4; ++k) {
;             const int c = 4 * g + k;
;             const float r = (float)(n0 + c) * invN;
;             const float2 yo = cmul(make_float2(hw_cos_rev(r), hw_sin_rev(r)), xc[c]);
;             const float2 ye = unpack_h2(yew[k]);
;             const float ya = ye.x + yo.x * (16.0f * invN), yb = ye.y + yo.y * (16.0f * invN);
;             oa[k] = conv_at(rga, c, lga, rga_, cga) * (ya + ska * ua4[k]);
;             ob[k] = conv_at(rgb, c, lgb, rgb_, cgb) * (yb + skb * ub4[k]);
;           }
;           { u32x2 wa, wb; wa.x = cvt_pk_bf16(oa[0], oa[1]); wa.y = cvt_pk_bf16(oa[2], oa[3]); wb.x = cvt_pk_bf16(ob[0], ob[1]); wb.y = cvt_pk_bf16(ob[2], ob[3]);
;             *(u32x2*)(za + n0 + 4 * g) = wa; *(u32x2*)(zb + n0 + 4 * g) = wb; }
.LBB0_137:
	v_or_b32_e32 v97, 8, v114
	v_cvt_f32_i32_e32 v97, v97
	ds_read2_b64 v[148:151], v115 offset0:8 offset1:9
	v_and_b32_e32 v134, 0xffff0000, v84
	v_or_b32_e32 v84, 9, v114
	v_mul_f32_e32 v97, 0x38000000, v97
	v_cos_f32_e32 v104, v97
	v_sin_f32_e32 v105, v97
	v_cvt_f32_i32_e32 v84, v84
	v_and_b32_e32 v88, 0xffff0000, v88
	s_waitcnt lgkmcnt(0)
	v_mul_f32_e32 v108, v104, v148
	v_pk_fma_f32 v[124:125], v[104:105], v[148:149], v[108:109] op_sel_hi:[1,1,0] neg_lo:[1,0,0] neg_hi:[1,0,0]
	v_mov_b32_e32 v126, v105
	v_mov_b32_e32 v127, v104
	v_mul_f32_e32 v104, v105, v148
	v_pk_fma_f32 v[128:129], v[126:127], v[148:149], v[104:105] op_sel_hi:[1,1,0]
	v_lshlrev_b32_e32 v105, 16, v197
	v_mul_f32_e32 v104, s34, v110
	v_mov_b32_e32 v153, v125
	v_add_f32_e32 v136, s59, v88
	v_pk_fma_f32 v[104:105], s[96:97], v[152:153], v[104:105]
	v_mov_b32_e32 v137, v98
	v_pk_fma_f32 v[104:105], s[40:41], v[136:137], v[104:105]
	v_mul_f32_e32 v84, 0x38000000, v84
	v_add_f32_e32 v88, s93, v104
	v_cos_f32_e32 v104, v84
	v_mul_f32_e32 v107, v88, v105
	v_sin_f32_e32 v105, v84
	v_lshlrev_b32_e32 v111, 16, v198
	v_mul_f32_e32 v84, v104, v150
	v_mov_b32_e32 v125, v104
	v_pk_fma_f32 v[140:141], v[104:105], v[150:151], v[84:85] op_sel_hi:[1,1,0] neg_lo:[1,0,0] neg_hi:[1,0,0]
	v_mov_b32_e32 v124, v105
	v_mul_f32_e32 v84, v105, v150
	v_pk_fma_f32 v[124:125], v[124:125], v[150:151], v[84:85] op_sel_hi:[1,1,0]
	v_lshlrev_b32_e32 v84, 16, v89
	v_mul_f32_e32 v110, s96, v110
	v_mov_b32_e32 v137, v141
	v_add_f32_e32 v98, s59, v84
	v_pk_fma_f32 v[110:111], s[34:35], v[136:137], v[110:111]
	ds_read2_b64 v[148:151], v115 offset0:10 offset1:11
	v_pk_fma_f32 v[110:111], s[40:41], v[98:99], v[110:111]
	v_lshlrev_b32_e32 v153, 16, v199
	v_add_f32_e32 v84, s93, v110
	v_mul_f32_e32 v108, v84, v111
	v_or_b32_e32 v84, 10, v114
	v_cvt_f32_i32_e32 v84, v84
	v_mul_f32_e32 v152, s34, v98
	v_and_b32_e32 v127, 0xffff0000, v197
	v_mul_f32_e32 v126, s94, v96
	v_mul_f32_e32 v84, 0x38000000, v84
	v_cos_f32_e32 v110, v84
	v_sin_f32_e32 v111, v84
	v_mov_b32_e32 v103, v129
	v_pk_fma_f32 v[102:103], s[26:27], v[102:103], v[126:127]
	s_waitcnt lgkmcnt(0)
	v_mul_f32_e32 v84, v110, v148
	v_pk_fma_f32 v[140:141], v[110:111], v[148:149], v[84:85] op_sel_hi:[1,1,0] neg_lo:[1,0,0] neg_hi:[1,0,0]
	v_and_b32_e32 v84, 0xffff0000, v89
	v_or_b32_e32 v89, 11, v114
	v_cvt_f32_i32_e32 v89, v89
	v_mul_f32_e32 v135, v110, v149
	v_mul_f32_e32 v111, v111, v148
	v_mov_b32_e32 v137, v141
	v_mov_b32_e32 v110, s65
	v_add_f32_e32 v148, s59, v84
	v_pk_fma_f32 v[136:137], s[96:97], v[136:137], v[152:153]
	v_mov_b32_e32 v149, v100
	v_pk_add_f32 v[134:135], v[110:111], v[134:135]
	v_pk_fma_f32 v[136:137], s[40:41], v[148:149], v[136:137]
	v_mov_b32_e32 v126, v134
	v_mov_b32_e32 v127, v92
	v_add_f32_e32 v84, s93, v136
	v_pk_fma_f32 v[102:103], s[46:47], v[126:127], v[102:103]
	v_mul_f32_e32 v89, 0x38000000, v89
	v_lshlrev_b32_e32 v88, 16, v85
	v_mul_f32_e32 v120, v84, v137
	v_and_b32_e32 v84, 0xffff0000, v85
	v_add_f32_e32 v85, s55, v102
	v_cos_f32_e32 v102, v89
	v_mul_f32_e32 v122, v85, v103
	v_sin_f32_e32 v103, v89
	v_and_b32_e32 v105, 0xffff0000, v198
	v_mul_f32_e32 v92, v102, v150
	v_mul_f32_e32 v89, v102, v151
	v_pk_fma_f32 v[126:127], v[102:103], v[150:151], v[92:93] op_sel_hi:[1,1,0] neg_lo:[1,0,0] neg_hi:[1,0,0]
	v_mul_f32_e32 v111, v103, v150
	v_lshlrev_b32_e32 v103, 16, v200
	v_lshlrev_b32_e32 v92, 16, v90
	v_mul_f32_e32 v102, s34, v148
	v_mov_b32_e32 v99, v127
	v_add_f32_e32 v100, s59, v92
	v_pk_fma_f32 v[98:99], s[96:97], v[98:99], v[102:103]
	v_mul_f32_e32 v104, s94, v134
	v_pk_fma_f32 v[98:99], s[40:41], v[100:101], v[98:99]
	v_pk_add_f32 v[88:89], v[110:111], v[88:89]
	v_add_f32_e32 v92, s93, v98
	v_mul_f32_e32 v98, v92, v99
	v_lshlrev_b32_e32 v92, 16, v86
	v_mov_b32_e32 v97, v125
	v_mov_b32_e32 v85, v94
	v_add_f32_e32 v94, s65, v92
	v_pk_fma_f32 v[96:97], s[26:27], v[96:97], v[104:105]
	v_mov_b32_e32 v92, v88
	v_add_f32_e32 v84, s65, v84
	v_pk_fma_f32 v[92:93], s[46:47], v[92:93], v[96:97]
	v_and_b32_e32 v155, 0xffff0000, v199
	v_and_b32_e32 v129, 0xffff0000, v200
	v_mul_f32_e32 v128, s94, v84
	v_mul_f32_e32 v154, s94, v88
	v_add_f32_e32 v92, s55, v92
	v_mul_f32_e32 v96, v92, v93
	v_pk_fma_f32 v[92:93], s[26:27], v[134:135], v[154:155]
	v_pk_fma_f32 v[88:89], s[26:27], v[88:89], v[128:129]
	v_pk_fma_f32 v[92:93], s[46:47], v[84:85], v[92:93]
	v_pk_fma_f32 v[88:89], s[46:47], v[94:95], v[88:89]
	v_add_f32_e32 v85, s55, v92
	v_add_f32_e32 v88, s55, v88
	v_mul_f32_e32 v85, v85, v93
	v_mul_f32_e32 v93, v88, v89
	v_cvt_pk_bf16_f32 v88, v107, v108
	v_cvt_pk_bf16_f32 v89, v120, v98
	s_mov_b64 s[10:11], -1
	s_and_b64 vcc, exec, s[6:7]
	v_cvt_pk_bf16_f32 v92, v122, v96
	v_cvt_pk_bf16_f32 v93, v85, v93
	global_store_dwordx2 v[116:117], v[88:89], off offset:16
	global_store_dwordx2 v[118:119], v[92:93], off offset:16
	s_cbranch_vccnz .LBB0_139
	v_mov_b32_e32 v88, v40
	v_mov_b32_e32 v89, v41
	v_mov_b32_e32 v92, v42
	v_mov_b32_e32 v93, v43
	s_mov_b64 s[10:11], 0
	s_nop 0
	v_lshlrev_b32_e32 v102, 16, v88
	v_and_b32_e32 v103, 0xffff0000, v88
	v_lshlrev_b32_e32 v104, 16, v89
	v_and_b32_e32 v105, 0xffff0000, v89
	s_nop 0
	v_lshlrev_b32_e32 v96, 16, v92
	v_and_b32_e32 v97, 0xffff0000, v92
	v_lshlrev_b32_e32 v98, 16, v93
	v_and_b32_e32 v99, 0xffff0000, v93

; __device__ __forceinline__ unsigned cvt_pk_bf16(float lo, float hi) { unsigned r; asm volatile("v_cvt_pk_bf16_f32 %0, %1, %2" : "=v"(r) : "v"(lo), "v"(hi)); return r; }
; __device__ __forceinline__ float hw_sin_rev(float r) { return __builtin_amdgcn_sinf(r); }
; __device__ __forceinline__ float hw_cos_rev(float r) { return __builtin_amdgcn_cosf(r); }
; __device__ __forceinline__ float2 cmul(float2 a, float2 b) { return make_float2(a.x * b.x - a.y * b.y, a.x * b.y + a.y * b.x); }
; __device__ __forceinline__ float2 unpack_h2(unsigned w) { return make_float2(__uint_as_float(w << 16), __uint_as_float(w & 0xffff0000u)); }
; template <int MODE> __device__ __forceinline__ void hyena_unit(KP p, int pair, float2* X, int wave_id) {
;     ...
;           } else { float a[4], b[4]; unpack4(*(const u32x2*)(za + n0 + 4 * g), a); unpack4(*(const u32x2*)(zb + n0 + 4 * g), b);
; #pragma unroll
;             for (int k = 0; k < 4; ++k) { ua4[k] = a[k]; ub4[k] = b[k]; } }
;           const u32x4 yew = (g < 7) ? yreg[g < 7 ? g : 0] : ylast;
;           f32x4 oa, ob;
; #pragma unroll
;           for (int k = 0; k < 4; ++k) {
;             const int c = 4 * g + k;
;             const float r = (float)(n0 + c) * invN;
;             const float2 yo = cmul(make_float2(hw_cos_rev(r), hw_sin_rev(r)), xc[c]);
;             const float2 ye = unpack_h2(yew[k]);
;             const float ya = ye.x + yo.x * (16.0f * invN), yb = ye.y + yo.y * (16.0f * invN);
;             oa[k] = conv_at(rga, c, lga, rga_, cga) * (ya + ska * ua4[k]);
;             ob[k] = conv_at(rgb, c, lgb, rgb_, cgb) * (yb + skb * ub4[k]);
;           }
;           { u32x2 wa, wb; wa.x = cvt_pk_bf16(oa[0], oa[1]); wa.y = cvt_pk_bf16(oa[2], oa[3]); wb.x = cvt_pk_bf16(ob[0], ob[1]); wb.y = cvt_pk_bf16(ob[2], ob[3]);
;             *(u32x2*)(za + n0 + 4 * g) = wa; *(u32x2*)(zb + n0 + 4 * g) = wb; }
.LBB0_141:
	v_or_b32_e32 v85, 12, v114
	v_cvt_f32_i32_e32 v85, v85
	ds_read2_b64 v[130:133], v115 offset0:12 offset1:13
	v_and_b32_e32 v101, 0xffff0000, v202
	v_and_b32_e32 v151, 0xffff0000, v203
	v_mul_f32_e32 v85, 0x38000000, v85
	v_cos_f32_e32 v106, v85
	v_sin_f32_e32 v107, v85
	v_and_b32_e32 v85, 0xffff0000, v90
	s_mov_b64 s[10:11], -1
	s_waitcnt lgkmcnt(0)
	v_mul_f32_e32 v120, v106, v130
	v_pk_fma_f32 v[128:129], v[106:107], v[130:131], v[120:121] op_sel_hi:[1,1,0] neg_lo:[1,0,0] neg_hi:[1,0,0]
	v_mov_b32_e32 v124, v107
	v_mov_b32_e32 v125, v106
	v_mul_f32_e32 v106, v107, v130
	v_pk_fma_f32 v[126:127], v[124:125], v[130:131], v[106:107] op_sel_hi:[1,1,0]
	v_lshlrev_b32_e32 v107, 16, v201
	v_mul_f32_e32 v106, s34, v100
	v_mov_b32_e32 v149, v129
	v_add_f32_e32 v130, s59, v85
	v_pk_fma_f32 v[106:107], s[96:97], v[148:149], v[106:107]
	v_mov_b32_e32 v131, v102
	v_pk_fma_f32 v[106:107], s[40:41], v[130:131], v[106:107]
	v_and_b32_e32 v128, 0xffff0000, v86
	v_add_f32_e32 v85, s93, v106
	v_mul_f32_e32 v89, v85, v107
	v_or_b32_e32 v85, 13, v114
	v_cvt_f32_i32_e32 v85, v85
	v_lshlrev_b32_e32 v149, 16, v203
	v_and_b32_e32 v125, 0xffff0000, v201
	v_mul_f32_e32 v124, s94, v94
	v_mul_f32_e32 v85, 0x38000000, v85
	v_cos_f32_e32 v106, v85
	v_sin_f32_e32 v107, v85
	v_lshlrev_b32_e32 v85, 16, v91
	v_add_f32_e32 v102, s59, v85
	v_mul_f32_e32 v86, v106, v132
	v_pk_fma_f32 v[134:135], v[106:107], v[132:133], v[86:87] op_sel_hi:[1,1,0] neg_lo:[1,0,0] neg_hi:[1,0,0]
	v_mov_b32_e32 v136, v107
	v_mov_b32_e32 v137, v106
	v_mul_f32_e32 v86, v107, v132
	v_pk_fma_f32 v[106:107], v[136:137], v[132:133], v[86:87] op_sel_hi:[1,1,0]
	v_lshlrev_b32_e32 v133, 16, v202
	v_mul_f32_e32 v132, s96, v100
	v_mov_b32_e32 v131, v135
	v_pk_fma_f32 v[132:133], s[34:35], v[130:131], v[132:133]
	ds_read2_b64 v[134:137], v115 offset0:14 offset1:15
	v_pk_fma_f32 v[132:133], s[40:41], v[102:103], v[132:133]
	v_mul_f32_e32 v148, s34, v102
	v_add_f32_e32 v85, s93, v132
	v_mul_f32_e32 v93, v85, v133
	v_or_b32_e32 v85, 14, v114
	v_cvt_f32_i32_e32 v85, v85
	v_lshlrev_b32_e32 v86, 16, v87
	v_mov_b32_e32 v95, v107
	s_and_b64 vcc, exec, s[6:7]
	v_mul_f32_e32 v85, 0x38000000, v85
	v_cos_f32_e32 v132, v85
	v_sin_f32_e32 v133, v85
	v_and_b32_e32 v85, 0xffff0000, v91
	s_waitcnt lgkmcnt(0)
	v_mul_f32_e32 v90, v132, v134
	v_pk_fma_f32 v[140:141], v[132:133], v[134:135], v[90:91] op_sel_hi:[1,1,0] neg_lo:[1,0,0] neg_hi:[1,0,0]
	v_mul_f32_e32 v129, v132, v135
	v_mov_b32_e32 v131, v141
	v_mul_f32_e32 v135, v133, v134
	v_add_f32_e32 v132, s59, v85
	v_pk_fma_f32 v[90:91], s[96:97], v[130:131], v[148:149]
	v_mov_b32_e32 v133, v104
	v_pk_fma_f32 v[90:91], s[40:41], v[132:133], v[90:91]
	v_mov_b32_e32 v134, s65
	v_add_f32_e32 v85, s93, v90
	v_mul_f32_e32 v106, v85, v91
	v_and_b32_e32 v85, 0xffff0000, v87
	v_add_f32_e32 v90, s65, v85
	v_pk_add_f32 v[128:129], v[134:135], v[128:129]
	v_mov_b32_e32 v85, v127
	v_pk_fma_f32 v[84:85], s[26:27], v[84:85], v[124:125]
	v_mov_b32_e32 v124, v128
	v_mov_b32_e32 v125, v96
	v_pk_fma_f32 v[84:85], s[46:47], v[124:125], v[84:85]
	v_mul_f32_e32 v100, s94, v128
	v_add_f32_e32 v84, s55, v84
	v_mul_f32_e32 v109, v84, v85
	v_or_b32_e32 v84, 15, v114
	v_cvt_f32_i32_e32 v84, v84
	v_mov_b32_e32 v91, v98
	v_and_b32_e32 v127, 0xffff0000, v204
	v_mul_f32_e32 v126, s94, v90
	v_mul_f32_e32 v85, 0x38000000, v84
	v_cos_f32_e32 v84, v85
	v_sin_f32_e32 v85, v85
	v_mul_f32_e32 v96, v84, v136
	v_pk_fma_f32 v[124:125], v[84:85], v[136:137], v[96:97] op_sel_hi:[1,1,0] neg_lo:[1,0,0] neg_hi:[1,0,0]
	v_mul_f32_e32 v87, v84, v137
	v_lshlrev_b32_e32 v84, 16, v80
	v_mul_f32_e32 v135, v85, v136
	v_lshlrev_b32_e32 v85, 16, v204
	v_add_f32_e32 v104, s59, v84
	v_mul_f32_e32 v84, s34, v132
	v_mov_b32_e32 v103, v125
	v_pk_fma_f32 v[84:85], s[96:97], v[102:103], v[84:85]
	s_nop 0
	v_pk_fma_f32 v[84:85], s[40:41], v[104:105], v[84:85]
	s_nop 0
	v_add_f32_e32 v84, s93, v84
	v_mul_f32_e32 v102, v84, v85
	v_lshlrev_b32_e32 v84, 16, v76
	v_add_f32_e32 v98, s65, v84
	v_pk_add_f32 v[84:85], v[134:135], v[86:87]
	v_pk_fma_f32 v[86:87], s[26:27], v[94:95], v[100:101]
	v_mov_b32_e32 v96, v84
	v_pk_fma_f32 v[86:87], s[46:47], v[96:97], v[86:87]
	v_mul_f32_e32 v150, s94, v84
	v_add_f32_e32 v86, s55, v86
	v_mul_f32_e32 v94, v86, v87
	v_pk_fma_f32 v[86:87], s[26:27], v[128:129], v[150:151]
	v_pk_fma_f32 v[84:85], s[26:27], v[84:85], v[126:127]
	v_pk_fma_f32 v[86:87], s[46:47], v[90:91], v[86:87]
	v_pk_fma_f32 v[84:85], s[46:47], v[98:99], v[84:85]
	v_add_f32_e32 v86, s55, v86
	v_mul_f32_e32 v87, v86, v87
	v_add_f32_e32 v84, s55, v84
	v_mul_f32_e32 v91, v84, v85
	v_cvt_pk_bf16_f32 v84, v89, v93
	v_cvt_pk_bf16_f32 v85, v106, v102
	v_cvt_pk_bf16_f32 v86, v109, v94
	v_cvt_pk_bf16_f32 v87, v87, v91
	global_store_dwordx2 v[116:117], v[84:85], off offset:24
	global_store_dwordx2 v[118:119], v[86:87], off offset:24
	s_cbranch_vccnz .LBB0_143
	v_mov_b32_e32 v84, v44
	v_mov_b32_e32 v85, v45
	v_mov_b32_e32 v86, v46
	v_mov_b32_e32 v87, v47
	s_mov_b64 s[10:11], 0
	s_nop 0
	v_lshlrev_b32_e32 v94, 16, v84
	v_and_b32_e32 v95, 0xffff0000, v84
	v_lshlrev_b32_e32 v96, 16, v85
	v_and_b32_e32 v97, 0xffff0000, v85
	s_nop 0
	v_lshlrev_b32_e32 v84, 16, v86
	v_and_b32_e32 v85, 0xffff0000, v86
	v_lshlrev_b32_e32 v86, 16, v87
	v_and_b32_e32 v87, 0xffff0000, v87

; __device__ __forceinline__ unsigned cvt_pk_bf16(float lo, float hi) { unsigned r; asm volatile("v_cvt_pk_bf16_f32 %0, %1, %2" : "=v"(r) : "v"(lo), "v"(hi)); return r; }
; __device__ __forceinline__ float hw_sin_rev(float r) { return __builtin_amdgcn_sinf(r); }
; __device__ __forceinline__ float hw_cos_rev(float r) { return __builtin_amdgcn_cosf(r); }
; __device__ __forceinline__ float2 cmul(float2 a, float2 b) { return make_float2(a.x * b.x - a.y * b.y, a.x * b.y + a.y * b.x); }
; __device__ __forceinline__ float2 unpack_h2(unsigned w) { return make_float2(__uint_as_float(w << 16), __uint_as_float(w & 0xffff0000u)); }
; template <int MODE> __device__ __forceinline__ void hyena_unit(KP p, int pair, float2* X, int wave_id) {
;     ...
;           } else { float a[4], b[4]; unpack4(*(const u32x2*)(za + n0 + 4 * g), a); unpack4(*(const u32x2*)(zb + n0 + 4 * g), b);
; #pragma unroll
;             for (int k = 0; k < 4; ++k) { ua4[k] = a[k]; ub4[k] = b[k]; } }
;           const u32x4 yew = (g < 7) ? yreg[g < 7 ? g : 0] : ylast;
;           f32x4 oa, ob;
; #pragma unroll
;           for (int k = 0; k < 4; ++k) {
;             const int c = 4 * g + k;
;             const float r = (float)(n0 + c) * invN;
;             const float2 yo = cmul(make_float2(hw_cos_rev(r), hw_sin_rev(r)), xc[c]);
;             const float2 ye = unpack_h2(yew[k]);
;             const float ya = ye.x + yo.x * (16.0f * invN), yb = ye.y + yo.y * (16.0f * invN);
;             oa[k] = conv_at(rga, c, lga, rga_, cga) * (ya + ska * ua4[k]);
;             ob[k] = conv_at(rgb, c, lgb, rgb_, cgb) * (yb + skb * ub4[k]);
;           }
;           { u32x2 wa, wb; wa.x = cvt_pk_bf16(oa[0], oa[1]); wa.y = cvt_pk_bf16(oa[2], oa[3]); wb.x = cvt_pk_bf16(ob[0], ob[1]); wb.y = cvt_pk_bf16(ob[2], ob[3]);
;             *(u32x2*)(za + n0 + 4 * g) = wa; *(u32x2*)(zb + n0 + 4 * g) = wb; }
.LBB0_145:
	v_or_b32_e32 v88, 16, v114
	v_cvt_f32_i32_e32 v88, v88
	ds_read2_b64 v[128:131], v115 offset0:16 offset1:17
	v_and_b32_e32 v126, 0xffff0000, v76
	v_or_b32_e32 v76, 17, v114
	v_mul_f32_e32 v89, 0x38000000, v88
	v_cos_f32_e32 v88, v89
	v_sin_f32_e32 v89, v89
	v_cvt_f32_i32_e32 v76, v76
	v_and_b32_e32 v80, 0xffff0000, v80
	s_waitcnt lgkmcnt(0)
	v_mul_f32_e32 v92, v88, v128
	v_pk_fma_f32 v[92:93], v[88:89], v[128:129], v[92:93] op_sel_hi:[1,1,0] neg_lo:[1,0,0] neg_hi:[1,0,0]
	v_mov_b32_e32 v108, v89
	v_mov_b32_e32 v109, v88
	v_mul_f32_e32 v88, v89, v128
	v_pk_fma_f32 v[110:111], v[108:109], v[128:129], v[88:89] op_sel_hi:[1,1,0]
	v_lshlrev_b32_e32 v89, 16, v205
	v_mul_f32_e32 v88, s34, v104
	v_mov_b32_e32 v133, v93
	v_add_f32_e32 v128, s59, v80
	v_pk_fma_f32 v[88:89], s[96:97], v[132:133], v[88:89]
	v_mov_b32_e32 v129, v94
	v_pk_fma_f32 v[88:89], s[40:41], v[128:129], v[88:89]
	v_mul_f32_e32 v76, 0x38000000, v76
	v_add_f32_e32 v80, s93, v88
	v_cos_f32_e32 v88, v76
	v_mul_f32_e32 v101, v80, v89
	v_sin_f32_e32 v89, v76
	v_lshlrev_b32_e32 v105, 16, v206
	v_mul_f32_e32 v76, v88, v130
	v_mov_b32_e32 v93, v88
	v_pk_fma_f32 v[132:133], v[88:89], v[130:131], v[76:77] op_sel_hi:[1,1,0] neg_lo:[1,0,0] neg_hi:[1,0,0]
	v_mov_b32_e32 v92, v89
	v_mul_f32_e32 v76, v89, v130
	v_pk_fma_f32 v[92:93], v[92:93], v[130:131], v[76:77] op_sel_hi:[1,1,0]
	v_lshlrev_b32_e32 v76, 16, v81
	v_mul_f32_e32 v104, s96, v104
	v_mov_b32_e32 v129, v133
	v_add_f32_e32 v94, s59, v76
	v_pk_fma_f32 v[104:105], s[34:35], v[128:129], v[104:105]
	ds_read2_b64 v[130:133], v115 offset0:18 offset1:19
	v_pk_fma_f32 v[104:105], s[40:41], v[94:95], v[104:105]
	v_lshlrev_b32_e32 v137, 16, v207
	v_add_f32_e32 v76, s93, v104
	v_mul_f32_e32 v92, v76, v105
	v_or_b32_e32 v76, 18, v114
	v_cvt_f32_i32_e32 v76, v76
	v_mul_f32_e32 v136, s34, v94
	v_and_b32_e32 v109, 0xffff0000, v205
	v_mul_f32_e32 v108, s94, v98
	v_mul_f32_e32 v76, 0x38000000, v76
	v_cos_f32_e32 v104, v76
	v_sin_f32_e32 v105, v76
	v_mov_b32_e32 v91, v111
	v_pk_fma_f32 v[90:91], s[26:27], v[90:91], v[108:109]
	s_waitcnt lgkmcnt(0)
	v_mul_f32_e32 v76, v104, v130
	v_pk_fma_f32 v[134:135], v[104:105], v[130:131], v[76:77] op_sel_hi:[1,1,0] neg_lo:[1,0,0] neg_hi:[1,0,0]
	v_and_b32_e32 v76, 0xffff0000, v81
	v_or_b32_e32 v81, 19, v114
	v_cvt_f32_i32_e32 v81, v81
	v_mul_f32_e32 v127, v104, v131
	v_mul_f32_e32 v105, v105, v130
	v_mov_b32_e32 v129, v135
	v_mov_b32_e32 v104, s65
	v_add_f32_e32 v130, s59, v76
	v_pk_fma_f32 v[128:129], s[96:97], v[128:129], v[136:137]
	v_mov_b32_e32 v131, v96
	v_pk_add_f32 v[126:127], v[104:105], v[126:127]
	v_pk_fma_f32 v[128:129], s[40:41], v[130:131], v[128:129]
	v_mov_b32_e32 v108, v126
	v_mov_b32_e32 v109, v84
	v_add_f32_e32 v76, s93, v128
	v_pk_fma_f32 v[90:91], s[46:47], v[108:109], v[90:91]
	v_mul_f32_e32 v81, 0x38000000, v81
	v_lshlrev_b32_e32 v80, 16, v77
	v_mul_f32_e32 v102, v76, v129
	v_and_b32_e32 v76, 0xffff0000, v77
	v_add_f32_e32 v77, s55, v90
	v_cos_f32_e32 v90, v81
	v_mul_f32_e32 v107, v77, v91
	v_sin_f32_e32 v91, v81
	v_and_b32_e32 v89, 0xffff0000, v206
	v_mul_f32_e32 v84, v90, v132
	v_mul_f32_e32 v81, v90, v133
	v_pk_fma_f32 v[108:109], v[90:91], v[132:133], v[84:85] op_sel_hi:[1,1,0] neg_lo:[1,0,0] neg_hi:[1,0,0]
	v_mul_f32_e32 v105, v91, v132
	v_lshlrev_b32_e32 v91, 16, v208
	v_lshlrev_b32_e32 v84, 16, v82
	v_mul_f32_e32 v90, s34, v130
	v_mov_b32_e32 v95, v109
	v_add_f32_e32 v96, s59, v84
	v_pk_fma_f32 v[90:91], s[96:97], v[94:95], v[90:91]
	v_mul_f32_e32 v88, s94, v126
	v_pk_fma_f32 v[90:91], s[40:41], v[96:97], v[90:91]
	v_pk_add_f32 v[80:81], v[104:105], v[80:81]
	v_add_f32_e32 v84, s93, v90
	v_mul_f32_e32 v90, v84, v91
	v_lshlrev_b32_e32 v84, 16, v78
	v_mov_b32_e32 v99, v93
	v_mov_b32_e32 v77, v86
	v_add_f32_e32 v86, s65, v84
	v_pk_fma_f32 v[88:89], s[26:27], v[98:99], v[88:89]
	v_mov_b32_e32 v84, v80
	v_add_f32_e32 v76, s65, v76
	v_pk_fma_f32 v[84:85], s[46:47], v[84:85], v[88:89]
	v_and_b32_e32 v141, 0xffff0000, v207
	v_and_b32_e32 v111, 0xffff0000, v208
	v_mul_f32_e32 v110, s94, v76
	v_mul_f32_e32 v140, s94, v80
	v_add_f32_e32 v84, s55, v84
	v_mul_f32_e32 v88, v84, v85
	v_pk_fma_f32 v[84:85], s[26:27], v[126:127], v[140:141]
	v_pk_fma_f32 v[80:81], s[26:27], v[80:81], v[110:111]
	v_pk_fma_f32 v[84:85], s[46:47], v[76:77], v[84:85]
	v_pk_fma_f32 v[80:81], s[46:47], v[86:87], v[80:81]
	v_add_f32_e32 v77, s55, v84
	v_add_f32_e32 v80, s55, v80
	v_mul_f32_e32 v77, v77, v85
	v_mul_f32_e32 v85, v80, v81
	v_cvt_pk_bf16_f32 v80, v101, v92
	v_cvt_pk_bf16_f32 v81, v102, v90
	s_mov_b64 s[10:11], -1
	s_and_b64 vcc, exec, s[6:7]
	v_cvt_pk_bf16_f32 v84, v107, v88
	v_cvt_pk_bf16_f32 v85, v77, v85
	global_store_dwordx2 v[116:117], v[80:81], off offset:32
	global_store_dwordx2 v[118:119], v[84:85], off offset:32
	s_cbranch_vccnz .LBB0_147
	v_mov_b32_e32 v80, v48
	v_mov_b32_e32 v81, v49
	v_mov_b32_e32 v84, v50
	v_mov_b32_e32 v85, v51
	s_mov_b64 s[10:11], 0
	s_nop 0
	v_lshlrev_b32_e32 v92, 16, v80
	v_and_b32_e32 v93, 0xffff0000, v80
	v_lshlrev_b32_e32 v94, 16, v81
	v_and_b32_e32 v95, 0xffff0000, v81
	s_nop 0
	v_lshlrev_b32_e32 v88, 16, v84
	v_and_b32_e32 v89, 0xffff0000, v84
	v_lshlrev_b32_e32 v90, 16, v85
	v_and_b32_e32 v91, 0xffff0000, v85

; __device__ __forceinline__ unsigned cvt_pk_bf16(float lo, float hi) { unsigned r; asm volatile("v_cvt_pk_bf16_f32 %0, %1, %2" : "=v"(r) : "v"(lo), "v"(hi)); return r; }
; __device__ __forceinline__ float hw_sin_rev(float r) { return __builtin_amdgcn_sinf(r); }
; __device__ __forceinline__ float hw_cos_rev(float r) { return __builtin_amdgcn_cosf(r); }
; __device__ __forceinline__ float2 cmul(float2 a, float2 b) { return make_float2(a.x * b.x - a.y * b.y, a.x * b.y + a.y * b.x); }
; __device__ __forceinline__ float2 unpack_h2(unsigned w) { return make_float2(__uint_as_float(w << 16), __uint_as_float(w & 0xffff0000u)); }
; template <int MODE> __device__ __forceinline__ void hyena_unit(KP p, int pair, float2* X, int wave_id) {
;     ...
;           } else { float a[4], b[4]; unpack4(*(const u32x2*)(za + n0 + 4 * g), a); unpack4(*(const u32x2*)(zb + n0 + 4 * g), b);
; #pragma unroll
;             for (int k = 0; k < 4; ++k) { ua4[k] = a[k]; ub4[k] = b[k]; } }
;           const u32x4 yew = (g < 7) ? yreg[g < 7 ? g : 0] : ylast;
;           f32x4 oa, ob;
; #pragma unroll
;           for (int k = 0; k < 4; ++k) {
;             const int c = 4 * g + k;
;             const float r = (float)(n0 + c) * invN;
;             const float2 yo = cmul(make_float2(hw_cos_rev(r), hw_sin_rev(r)), xc[c]);
;             const float2 ye = unpack_h2(yew[k]);
;             const float ya = ye.x + yo.x * (16.0f * invN), yb = ye.y + yo.y * (16.0f * invN);
;             oa[k] = conv_at(rga, c, lga, rga_, cga) * (ya + ska * ua4[k]);
;             ob[k] = conv_at(rgb, c, lgb, rgb_, cgb) * (yb + skb * ub4[k]);
;           }
;           { u32x2 wa, wb; wa.x = cvt_pk_bf16(oa[0], oa[1]); wa.y = cvt_pk_bf16(oa[2], oa[3]); wb.x = cvt_pk_bf16(ob[0], ob[1]); wb.y = cvt_pk_bf16(ob[2], ob[3]);
;             *(u32x2*)(za + n0 + 4 * g) = wa; *(u32x2*)(zb + n0 + 4 * g) = wb; }
.LBB0_149:
	v_or_b32_e32 v77, 20, v114
	v_cvt_f32_i32_e32 v77, v77
	ds_read2_b64 v[124:127], v115 offset0:20 offset1:21
	v_mov_b32_e32 v111, v92
	v_lshlrev_b32_e32 v133, 16, v246
	v_mul_f32_e32 v77, 0x38000000, v77
	v_cos_f32_e32 v100, v77
	v_sin_f32_e32 v101, v77
	v_and_b32_e32 v77, 0xffff0000, v82
	v_add_f32_e32 v110, s59, v77
	s_waitcnt lgkmcnt(0)
	v_mul_f32_e32 v102, v100, v124
	v_pk_fma_f32 v[108:109], v[100:101], v[124:125], v[102:103] op_sel_hi:[1,1,0] neg_lo:[1,0,0] neg_hi:[1,0,0]
	v_mov_b32_e32 v102, v101
	v_mov_b32_e32 v103, v100
	v_mul_f32_e32 v100, v101, v124
	v_pk_fma_f32 v[106:107], v[102:103], v[124:125], v[100:101] op_sel_hi:[1,1,0]
	v_lshlrev_b32_e32 v101, 16, v209
	v_mul_f32_e32 v100, s34, v96
	v_mov_b32_e32 v131, v109
	v_pk_fma_f32 v[100:101], s[96:97], v[130:131], v[100:101]
	v_and_b32_e32 v108, 0xffff0000, v78
	v_pk_fma_f32 v[100:101], s[40:41], v[110:111], v[100:101]
	v_and_b32_e32 v103, 0xffff0000, v209
	v_add_f32_e32 v77, s93, v100
	v_mul_f32_e32 v81, v77, v101
	v_or_b32_e32 v77, 21, v114
	v_cvt_f32_i32_e32 v77, v77
	v_mul_f32_e32 v102, s94, v86
	v_and_b32_e32 v97, 0xffff0000, v245
	v_and_b32_e32 v135, 0xffff0000, v246
	v_mul_f32_e32 v77, 0x38000000, v77
	v_cos_f32_e32 v100, v77
	v_sin_f32_e32 v101, v77
	v_lshlrev_b32_e32 v77, 16, v83
	v_add_f32_e32 v92, s59, v77
	v_mul_f32_e32 v78, v100, v126
	v_pk_fma_f32 v[124:125], v[100:101], v[126:127], v[78:79] op_sel_hi:[1,1,0] neg_lo:[1,0,0] neg_hi:[1,0,0]
	v_mov_b32_e32 v128, v101
	v_mov_b32_e32 v129, v100
	v_mul_f32_e32 v78, v101, v126
	v_pk_fma_f32 v[100:101], v[128:129], v[126:127], v[78:79] op_sel_hi:[1,1,0]
	v_lshlrev_b32_e32 v127, 16, v245
	v_mul_f32_e32 v126, s96, v96
	v_mov_b32_e32 v111, v125
	v_pk_fma_f32 v[124:125], s[34:35], v[110:111], v[126:127]
	ds_read2_b64 v[126:129], v115 offset0:22 offset1:23
	v_pk_fma_f32 v[124:125], s[40:41], v[92:93], v[124:125]
	v_mul_f32_e32 v132, s34, v92
	v_add_f32_e32 v77, s93, v124
	v_mul_f32_e32 v85, v77, v125
	v_or_b32_e32 v77, 22, v114
	v_cvt_f32_i32_e32 v77, v77
	v_lshlrev_b32_e32 v78, 16, v79
	v_mov_b32_e32 v87, v101
	s_mov_b64 s[10:11], -1
	v_mul_f32_e32 v77, 0x38000000, v77
	v_cos_f32_e32 v124, v77
	v_sin_f32_e32 v125, v77
	v_and_b32_e32 v77, 0xffff0000, v83
	s_and_b64 vcc, exec, s[6:7]
	s_waitcnt lgkmcnt(0)
	v_mul_f32_e32 v82, v124, v126
	v_pk_fma_f32 v[130:131], v[124:125], v[126:127], v[82:83] op_sel_hi:[1,1,0] neg_lo:[1,0,0] neg_hi:[1,0,0]
	v_mul_f32_e32 v109, v124, v127
	v_mov_b32_e32 v111, v131
	v_mul_f32_e32 v127, v125, v126
	v_add_f32_e32 v124, s59, v77
	v_pk_fma_f32 v[82:83], s[96:97], v[110:111], v[132:133]
	v_mov_b32_e32 v125, v94
	v_pk_fma_f32 v[82:83], s[40:41], v[124:125], v[82:83]
	v_mov_b32_e32 v126, s65
	v_add_f32_e32 v77, s93, v82
	v_mul_f32_e32 v99, v77, v83
	v_and_b32_e32 v77, 0xffff0000, v79
	v_add_f32_e32 v82, s65, v77
	v_pk_add_f32 v[108:109], v[126:127], v[108:109]
	v_mov_b32_e32 v77, v107
	v_pk_fma_f32 v[76:77], s[26:27], v[76:77], v[102:103]
	v_mov_b32_e32 v102, v108
	v_mov_b32_e32 v103, v88
	v_pk_fma_f32 v[76:77], s[46:47], v[102:103], v[76:77]
	v_mul_f32_e32 v96, s94, v108
	v_add_f32_e32 v76, s55, v76
	v_mul_f32_e32 v100, v76, v77
	v_or_b32_e32 v76, 23, v114
	v_cvt_f32_i32_e32 v76, v76
	v_mov_b32_e32 v83, v90
	v_and_b32_e32 v107, 0xffff0000, v247
	v_mul_f32_e32 v106, s94, v82
	v_mul_f32_e32 v77, 0x38000000, v76
	v_cos_f32_e32 v76, v77
	v_sin_f32_e32 v77, v77
	v_mul_f32_e32 v88, v76, v128
	v_pk_fma_f32 v[102:103], v[76:77], v[128:129], v[88:89] op_sel_hi:[1,1,0] neg_lo:[1,0,0] neg_hi:[1,0,0]
	v_mul_f32_e32 v79, v76, v129
	v_lshlrev_b32_e32 v76, 16, v68
	v_mul_f32_e32 v127, v77, v128
	v_lshlrev_b32_e32 v77, 16, v247
	v_add_f32_e32 v94, s59, v76
	v_mul_f32_e32 v76, s34, v124
	v_mov_b32_e32 v93, v103
	v_pk_fma_f32 v[76:77], s[96:97], v[92:93], v[76:77]
	s_nop 0
	v_pk_fma_f32 v[76:77], s[40:41], v[94:95], v[76:77]
	s_nop 0
	v_add_f32_e32 v76, s93, v76
	v_mul_f32_e32 v92, v76, v77
	v_lshlrev_b32_e32 v76, 16, v64
	v_add_f32_e32 v90, s65, v76
	v_pk_add_f32 v[76:77], v[126:127], v[78:79]
	v_pk_fma_f32 v[78:79], s[26:27], v[86:87], v[96:97]
	v_mov_b32_e32 v88, v76
	v_pk_fma_f32 v[78:79], s[46:47], v[88:89], v[78:79]
	v_mul_f32_e32 v134, s94, v76
	v_add_f32_e32 v78, s55, v78
	v_mul_f32_e32 v86, v78, v79
	v_pk_fma_f32 v[78:79], s[26:27], v[108:109], v[134:135]
	v_pk_fma_f32 v[76:77], s[26:27], v[76:77], v[106:107]
	v_pk_fma_f32 v[78:79], s[46:47], v[82:83], v[78:79]
	v_pk_fma_f32 v[76:77], s[46:47], v[90:91], v[76:77]
	v_add_f32_e32 v78, s55, v78
	v_mul_f32_e32 v79, v78, v79
	v_add_f32_e32 v76, s55, v76
	v_mul_f32_e32 v83, v76, v77
	v_cvt_pk_bf16_f32 v76, v81, v85
	v_cvt_pk_bf16_f32 v77, v99, v92
	v_cvt_pk_bf16_f32 v78, v100, v86
	v_cvt_pk_bf16_f32 v79, v79, v83
	global_store_dwordx2 v[116:117], v[76:77], off offset:40
	global_store_dwordx2 v[118:119], v[78:79], off offset:40
	s_cbranch_vccnz .LBB0_151
	v_mov_b32_e32 v76, v52
	v_mov_b32_e32 v77, v53
	v_mov_b32_e32 v78, v54
	v_mov_b32_e32 v79, v55
	s_mov_b64 s[10:11], 0
	s_nop 0
	v_lshlrev_b32_e32 v86, 16, v76
	v_and_b32_e32 v87, 0xffff0000, v76
	v_lshlrev_b32_e32 v88, 16, v77
	v_and_b32_e32 v89, 0xffff0000, v77
	s_nop 0
	v_lshlrev_b32_e32 v76, 16, v78
	v_and_b32_e32 v77, 0xffff0000, v78
	v_lshlrev_b32_e32 v78, 16, v79
	v_and_b32_e32 v79, 0xffff0000, v79

; __device__ __forceinline__ unsigned cvt_pk_bf16(float lo, float hi) { unsigned r; asm volatile("v_cvt_pk_bf16_f32 %0, %1, %2" : "=v"(r) : "v"(lo), "v"(hi)); return r; }
; __device__ __forceinline__ float hw_sin_rev(float r) { return __builtin_amdgcn_sinf(r); }
; __device__ __forceinline__ float hw_cos_rev(float r) { return __builtin_amdgcn_cosf(r); }
; __device__ __forceinline__ float2 cmul(float2 a, float2 b) { return make_float2(a.x * b.x - a.y * b.y, a.x * b.y + a.y * b.x); }
; __device__ __forceinline__ float2 unpack_h2(unsigned w) { return make_float2(__uint_as_float(w << 16), __uint_as_float(w & 0xffff0000u)); }
; template <int MODE> __device__ __forceinline__ void hyena_unit(KP p, int pair, float2* X, int wave_id) {
;     ...
;           } else { float a[4], b[4]; unpack4(*(const u32x2*)(za + n0 + 4 * g), a); unpack4(*(const u32x2*)(zb + n0 + 4 * g), b);
; #pragma unroll
;             for (int k = 0; k < 4; ++k) { ua4[k] = a[k]; ub4[k] = b[k]; } }
;           const u32x4 yew = (g < 7) ? yreg[g < 7 ? g : 0] : ylast;
;           f32x4 oa, ob;
; #pragma unroll
;           for (int k = 0; k < 4; ++k) {
;             const int c = 4 * g + k;
;             const float r = (float)(n0 + c) * invN;
;             const float2 yo = cmul(make_float2(hw_cos_rev(r), hw_sin_rev(r)), xc[c]);
;             const float2 ye = unpack_h2(yew[k]);
;             const float ya = ye.x + yo.x * (16.0f * invN), yb = ye.y + yo.y * (16.0f * invN);
;             oa[k] = conv_at(rga, c, lga, rga_, cga) * (ya + ska * ua4[k]);
;             ob[k] = conv_at(rgb, c, lgb, rgb_, cgb) * (yb + skb * ub4[k]);
;           }
;           { u32x2 wa, wb; wa.x = cvt_pk_bf16(oa[0], oa[1]); wa.y = cvt_pk_bf16(oa[2], oa[3]); wb.x = cvt_pk_bf16(ob[0], ob[1]); wb.y = cvt_pk_bf16(ob[2], ob[3]);
;             *(u32x2*)(za + n0 + 4 * g) = wa; *(u32x2*)(zb + n0 + 4 * g) = wb; }
.LBB0_153:
	v_or_b32_e32 v80, 24, v114
	v_cvt_f32_i32_e32 v80, v80
	ds_read2_b64 v[104:107], v115 offset0:24 offset1:25
	ds_read2_b64 v[108:111], v115 offset0:26 offset1:27
	v_and_b32_e32 v68, 0xffff0000, v68
	v_mul_f32_e32 v81, 0x38000000, v80
	v_cos_f32_e32 v80, v81
	v_sin_f32_e32 v81, v81
	v_lshlrev_b32_e32 v95, 16, v249
	v_and_b32_e32 v127, 0xffff0000, v248
	s_waitcnt lgkmcnt(1)
	v_mul_f32_e32 v84, v80, v104
	v_mov_b32_e32 v98, v81
	v_mov_b32_e32 v99, v80
	v_mul_f32_e32 v96, v81, v104
	v_pk_fma_f32 v[80:81], v[80:81], v[104:105], v[84:85] op_sel_hi:[1,1,0] neg_lo:[1,0,0] neg_hi:[1,0,0]
	v_pk_fma_f32 v[84:85], v[98:99], v[104:105], v[96:97] op_sel_hi:[1,1,0]
	v_add_f32_e32 v80, s59, v68
	v_or_b32_e32 v68, 25, v114
	v_cvt_f32_i32_e32 v68, v68
	v_lshlrev_b32_e32 v99, 16, v248
	v_mul_f32_e32 v98, s34, v94
	v_mov_b32_e32 v125, v81
	v_pk_fma_f32 v[98:99], s[96:97], v[124:125], v[98:99]
	v_mov_b32_e32 v81, v86
	v_pk_fma_f32 v[98:99], s[40:41], v[80:81], v[98:99]
	v_mul_f32_e32 v68, 0x38000000, v68
	v_add_f32_e32 v81, s93, v98
	v_cos_f32_e32 v98, v68
	v_mul_f32_e32 v93, v81, v99
	v_sin_f32_e32 v99, v68
	v_and_b32_e32 v124, 0xffff0000, v64
	v_mul_f32_e32 v64, v98, v106
	v_mov_b32_e32 v129, v98
	v_pk_fma_f32 v[104:105], v[98:99], v[106:107], v[64:65] op_sel_hi:[1,1,0] neg_lo:[1,0,0] neg_hi:[1,0,0]
	v_mov_b32_e32 v128, v99
	v_mul_f32_e32 v64, v99, v106
	v_pk_fma_f32 v[98:99], v[128:129], v[106:107], v[64:65] op_sel_hi:[1,1,0]
	v_lshlrev_b32_e32 v64, 16, v69
	v_add_f32_e32 v86, s59, v64
	v_or_b32_e32 v64, 26, v114
	v_cvt_f32_i32_e32 v64, v64
	v_mul_f32_e32 v94, s96, v94
	v_mov_b32_e32 v81, v105
	v_pk_fma_f32 v[94:95], s[34:35], v[80:81], v[94:95]
	v_mul_f32_e32 v64, 0x38000000, v64
	v_cos_f32_e32 v104, v64
	v_sin_f32_e32 v105, v64
	v_pk_fma_f32 v[94:95], s[40:41], v[86:87], v[94:95]
	v_lshlrev_b32_e32 v129, 16, v250
	v_add_f32_e32 v68, s93, v94
	s_waitcnt lgkmcnt(0)
	v_mul_f32_e32 v64, v104, v108
	v_mul_f32_e32 v96, v68, v95
	v_pk_fma_f32 v[94:95], v[104:105], v[108:109], v[64:65] op_sel_hi:[1,1,0] neg_lo:[1,0,0] neg_hi:[1,0,0]
	v_and_b32_e32 v64, 0xffff0000, v69
	v_mul_f32_e32 v128, s34, v86
	v_mov_b32_e32 v81, v95
	v_mul_f32_e32 v125, v104, v109
	v_mul_f32_e32 v109, v105, v108
	v_add_f32_e32 v104, s59, v64
	v_pk_fma_f32 v[80:81], s[96:97], v[80:81], v[128:129]
	v_mov_b32_e32 v105, v88
	v_pk_fma_f32 v[80:81], s[40:41], v[104:105], v[80:81]
	v_lshlrev_b32_e32 v68, 16, v65
	v_add_f32_e32 v64, s93, v80
	v_mul_f32_e32 v98, v64, v81
	v_and_b32_e32 v64, 0xffff0000, v65
	v_or_b32_e32 v65, 27, v114
	v_cvt_f32_i32_e32 v65, v65
	v_mov_b32_e32 v108, s65
	v_mul_f32_e32 v126, s94, v90
	v_pk_add_f32 v[80:81], v[108:109], v[124:125]
	v_mov_b32_e32 v83, v85
	v_pk_fma_f32 v[82:83], s[26:27], v[82:83], v[126:127]
	v_mov_b32_e32 v84, v80
	v_mov_b32_e32 v85, v76
	v_pk_fma_f32 v[82:83], s[46:47], v[84:85], v[82:83]
	v_mul_f32_e32 v65, 0x38000000, v65
	v_add_f32_e32 v69, s55, v82
	v_cos_f32_e32 v82, v65
	v_mul_f32_e32 v101, v69, v83
	v_sin_f32_e32 v83, v65
	v_and_b32_e32 v107, 0xffff0000, v249
	v_mul_f32_e32 v76, v82, v110
	v_mul_f32_e32 v69, v82, v111
	v_pk_fma_f32 v[84:85], v[82:83], v[110:111], v[76:77] op_sel_hi:[1,1,0] neg_lo:[1,0,0] neg_hi:[1,0,0]
	v_mul_f32_e32 v109, v83, v110
	v_lshlrev_b32_e32 v83, 16, v251
	v_lshlrev_b32_e32 v76, 16, v70
	v_mul_f32_e32 v82, s34, v104
	v_mov_b32_e32 v87, v85
	v_add_f32_e32 v88, s59, v76
	v_pk_fma_f32 v[82:83], s[96:97], v[86:87], v[82:83]
	v_mul_f32_e32 v106, s94, v80
	v_pk_fma_f32 v[82:83], s[40:41], v[88:89], v[82:83]
	v_pk_add_f32 v[68:69], v[108:109], v[68:69]
	v_add_f32_e32 v76, s93, v82
	v_mul_f32_e32 v84, v76, v83
	v_lshlrev_b32_e32 v76, 16, v66
	v_mov_b32_e32 v91, v99
	v_mov_b32_e32 v65, v78
	v_add_f32_e32 v78, s65, v76
	v_pk_fma_f32 v[82:83], s[26:27], v[90:91], v[106:107]
	v_mov_b32_e32 v76, v68
	v_add_f32_e32 v64, s65, v64
	v_pk_fma_f32 v[76:77], s[46:47], v[76:77], v[82:83]
	v_and_b32_e32 v131, 0xffff0000, v250
	v_and_b32_e32 v95, 0xffff0000, v251
	v_mul_f32_e32 v94, s94, v64
	v_mul_f32_e32 v130, s94, v68
	v_add_f32_e32 v76, s55, v76
	v_mul_f32_e32 v82, v76, v77
	v_pk_fma_f32 v[76:77], s[26:27], v[80:81], v[130:131]
	v_pk_fma_f32 v[68:69], s[26:27], v[68:69], v[94:95]
	v_pk_fma_f32 v[76:77], s[46:47], v[64:65], v[76:77]
	v_pk_fma_f32 v[68:69], s[46:47], v[78:79], v[68:69]
	v_add_f32_e32 v65, s55, v76
	v_add_f32_e32 v68, s55, v68
	v_mul_f32_e32 v65, v65, v77
	v_mul_f32_e32 v77, v68, v69
	v_cvt_pk_bf16_f32 v68, v93, v96
	v_cvt_pk_bf16_f32 v69, v98, v84
	s_and_b64 vcc, exec, s[6:7]
	s_mov_b64 s[6:7], -1
	v_cvt_pk_bf16_f32 v76, v101, v82
	v_cvt_pk_bf16_f32 v77, v65, v77
	global_store_dwordx2 v[116:117], v[68:69], off offset:48
	global_store_dwordx2 v[118:119], v[76:77], off offset:48
	s_cbranch_vccnz .LBB0_155
	v_mov_b32_e32 v68, v56
	v_mov_b32_e32 v69, v57
	v_mov_b32_e32 v76, v58
	v_mov_b32_e32 v77, v59
	s_mov_b64 s[6:7], 0
	s_nop 0
	v_lshlrev_b32_e32 v84, 16, v68
	v_and_b32_e32 v85, 0xffff0000, v68
	v_lshlrev_b32_e32 v86, 16, v69
	v_and_b32_e32 v87, 0xffff0000, v69
	s_nop 0
	v_lshlrev_b32_e32 v80, 16, v76
	v_and_b32_e32 v81, 0xffff0000, v76
	v_lshlrev_b32_e32 v82, 16, v77
	v_and_b32_e32 v83, 0xffff0000, v77
